# as v40 plus gridDim==256 guards on the static idle-window weight conversion (falls back to full prologue conversion otherwise)
# baseline (speedup 1.0000x reference)
;     __device__ __forceinline__ const float* in(int i) const { return (const float*)(const GAS float*)raw(i); }
;     __device__ __forceinline__ unsigned char* ws() const { return (unsigned char*)(GAS unsigned char*)raw(N_INPUTS + 1); }
; __device__ __forceinline__ CvItem cv_decode(const PT& a, int l, int r) {
;     unsigned char* ws = a.ws(); CvItem it;
;     if (r < IT_WIN) { const int kb = r / 458, nb = r % 458, n0 = nb * 32;
;         int drow; if (n0 < 2048) drow = n0; else if (n0 < 5120) drow = NIN_MAIN + (n0 - 2048); else if (n0 < 8512) drow = 2048 + (n0 - 5120); else drow = 5632 + (n0 - 8512);
;         it = CvItem{a.in(I_W_IN) + (size_t)l * D * NIN, NIN, kb * 64, n0, (bf16_t*)(ws + WS_WIN + l * WIN_L), D, drow, a.in(I_NORM_MIX_G) + l * D}; return it; }
;     r -= IT_WIN;
;     if (r < 3 * IT_BR) { const int br = r / IT_BR; r -= br * IT_BR; const int kb = r / 64, nb = r % 64;
;         it = CvItem{a.in(br == 0 ? I_W_BR_A : (br == 1 ? I_W_BR_B : I_W_BR_C)) + (size_t)l * 1024 * D, D, kb * 64, nb * 32, (bf16_t*)(ws + WS_WBR + l * WBR_L) + (size_t)br * D * 1024, 1024, nb * 32, nullptr}; return it; }
;     r -= 3 * IT_BR;
;     if (r < IT_OUT) { const int kb = r / 64, nb = r % 64;
;         it = CvItem{a.in(I_W_OUT) + (size_t)l * D * D, D, kb * 64, nb * 32, (bf16_t*)(ws + WS_WOUT + l * WOUT_L), D, nb * 32, nullptr}; return it; }
;     r -= IT_OUT;
;     if (r < 2 * IT_GU) { const int up = r / IT_GU; r -= up * IT_GU; const int kb = r / 176, nb = r % 176, n0 = nb * 32;
;         it = CvItem{a.in(up ? I_W_FFN_UP : I_W_FFN_GATE) + (size_t)l * D * DFF, DFF, kb * 64, n0, (bf16_t*)(ws + WS_WGU + l * WGU_L), D, 256 * (n0 / 128) + (n0 % 128) + 128 * up, a.in(I_NORM_FFN_G) + l * D}; return it; }
;     r -= 2 * IT_GU;
;     { const int kb = r / 64, nb = r % 64;
;       it = CvItem{a.in(I_W_FFN_DOWN) + (size_t)l * DFF * D, D, kb * 64, nb * 32, (bf16_t*)(ws + WS_WDN + l * WDN_L), DFF, nb * 32, nullptr}; }
;     return it;
; }
; __device__ __forceinline__ void prologue_a(const PT& a, LAS unsigned char* lds) {
;     ...
;     convert_layer_static(a, lds, 0, gw, NGW, wave, lane);
;     for (int cl_ = 1; cl_ < DEPTH; ++cl_) convert_layer_static(a, lds, cl_, gw, NGW, wave, lane, CV_PRO_ITEMS);
.LBB0_110:
	s_or_b64 exec, exec, s[12:13]
	v_lshl_add_u32 v2, v74, 2, v115
	v_add_u32_e32 v3, v115, v113
	s_mov_b32 s13, 0
	v_lshl_add_u32 v113, v67, 2, v3
	v_lshl_add_u32 v115, v69, 2, v3
	v_lshl_add_u32 v117, v97, 2, v3
	v_lshl_add_u32 v119, v99, 2, v3
	s_mov_b32 s18, 1
	s_lshl_b32 s42, s17, 5
	s_movk_i32 s43, 0x393f
	s_movk_i32 s44, 0x453f
	s_movk_i32 s45, 0x4d3f
	s_movk_i32 s46, 0x793f
	s_movk_i32 s47, 0x15ff
	s_movk_i32 s48, 0xba3
	s_movk_i32 s49, 0x1600
	s_movk_i32 s50, 0x3ff
	v_mov_b32_e32 v79, 0
	s_mov_b64 s[20:21], 0xea00000
	s_mov_b32 s51, 0x478bbced
	s_movk_i32 s52, 0x9f
	s_movk_i32 s53, 0x109
	v_add_u32_e32 v121, v2, v121
	v_lshlrev_b64 v[76:77], 1, v[76:77]
	s_mov_b32 s54, 0x673f
	v_readlane_b32 s100, v252, 4
	s_cmp_eq_u32 s100, 0x100
	s_cselect_b32 s54, s54, 0x8f3f
	v_mov_b32_e32 v123, 0xea00
	v_mov_b32_e32 v125, 5
	v_mov_b32_e32 v128, 0x23a40
	v_mov_b32_e32 v129, 0x23a38
	v_mov_b32_e32 v130, 6
	v_mov_b32_e32 v131, 0x80
	v_mov_b32_e32 v132, 0x23a20
	v_mov_b32_e32 v133, 0x23a18
	v_mov_b32_e32 v134, 0x23a10
	s_branch .LBB0_112

; #define LAS __attribute__((address_space(3)))
; __device__ __forceinline__ void cv_pair(const PT& a, LAS unsigned char* lds, int l, int r, int wave, int lane) {
;     LAS float* s0 = (LAS float*)(lds + wave * CV_WAVE_B); LAS float* s1 = (LAS float*)(lds + wave * CV_WAVE_B + CV_TILE_B);
;     const bool two = r + 1 < IT_LAYER;
;     const CvItem i0 = cv_decode(a, l, r), i1 = cv_decode(a, l, two ? r + 1 : r);
;     f32x4 v0[8], v1[8]; float g0[8], g1[8];
;     cv_load(i0, lane, v0, g0); cv_load(i1, lane, v1, g1);
;     cv_lds_write(s0, lane, v0, g0); cv_lds_write(s1, lane, v1, g1);
;     for (int it = 0; it < budget; ++it) {
;         unsigned r = 0; if (lane == 0) r = __hip_atomic_fetch_add(ctr, 2u, __ATOMIC_RELAXED, __HIP_MEMORY_SCOPE_AGENT);
;         r = (unsigned)__builtin_amdgcn_readfirstlane((int)r) + (unsigned)CV_PRO_ITEMS;
;         if (r >= (unsigned)IT_LAYER) break;
;         cv_pair(a, lds, l, (int)r, wave, lane);
;     }
; }
.LBB0_560:
	v_readlane_b32 s0, v252, 4
	s_cmp_lg_u32 s0, 0x100
	s_cbranch_scc1 .LcvqA_ret
	v_readlane_b32 s0, v252, 0
	v_readlane_b32 s36, v255, 0
	s_cmp_lt_u32 s0, 64
	s_cbranch_scc1 .LcvqA_ret
	s_cmp_gt_u32 s36, 2
	s_cbranch_scc1 .LcvqA_ret
	s_mov_b32 s64, s36
	v_readlane_b32 s0, v254, 53
	v_readlane_b32 s1, v254, 54
	s_mov_b32 s3, s1
	s_lshl_b32 s2, s36, 6
	s_lshl_b64 s[0:1], s[2:3], 2
	v_readlane_b32 s4, v254, 60
	v_readlane_b32 s5, v254, 61
	s_add_u32 s0, s4, s0
	s_addc_u32 s1, s5, s1
	s_add_u32 s0, s0, 0x8000
	s_addc_u32 s1, s1, 0
	s_add_i32 s2, s36, 1
	s_mul_hi_u32 s33, s2, 0x2c00000
	s_mul_i32 s34, s2, 0x2c00000
	s_mul_hi_u32 s35, s2, 0x1600000
	s_mul_i32 s50, s2, 0x1600000
	s_lshl_b32 s6, s2, 11
	s_mov_b32 s7, s3
	s_lshl_b64 s[8:9], s[2:3], 24
	s_lshl_b64 s[10:11], s[2:3], 23
	s_mul_hi_u32 s51, s2, 0xc00000
	s_mul_i32 s52, s2, 0xc00000
	s_mul_hi_u32 s53, s2, 0x7280000
	s_mul_i32 s54, s2, 0x7280000
	s_mul_hi_u32 s55, s2, 0x3a00000
	v_writelane_b32 v254, s2, 53
	v_mov_b32_e32 v2, v0
	s_mul_i32 s56, s2, 0x3a00000
	v_writelane_b32 v254, s3, 54
	s_waitcnt vmcnt(0) lgkmcnt(0)
	s_barrier
	s_movk_i32 s2, 0x4200
	v_lshrrev_b32_e32 v1, 6, v2
	v_and_b32_e32 v3, 63, v2
	v_readfirstlane_b32 s100, v1
	v_readlane_b32 s101, v252, 0
	s_sub_u32 s101, s101, 64
	s_lshl_b32 s101, s101, 3
	s_add_u32 s100, s100, s101
	s_lshl_b32 s100, s100, 1
	s_add_u32 s100, s100, 0x0
	v_mul_lo_u32 v1, v1, s2
	v_cmp_eq_u32_e64 s[40:41], 0, v3
	v_add_u32_e32 v3, 0, v1
	v_lshlrev_b32_e32 v1, 2, v2
	v_and_b32_e32 v66, 28, v1
	v_bfe_u32 v1, v2, 3, 3
	v_lshlrev_b32_e32 v2, 3, v2
	v_and_b32_e32 v68, 56, v2
	v_lshl_add_u32 v4, v66, 2, v3
	v_mul_u32_u24_e32 v5, 0x84, v1
	v_mul_u32_u24_e32 v2, 0x84, v68
	v_lshlrev_b32_e32 v6, 2, v1
	v_or_b32_e32 v67, 8, v1
	v_or_b32_e32 v69, 16, v1
	v_or_b32_e32 v71, 24, v1
	v_or_b32_e32 v73, 32, v1
	v_or_b32_e32 v75, 40, v1
	v_or_b32_e32 v77, 48, v1
	v_or_b32_e32 v79, 56, v1
	v_add3_u32 v81, v3, v2, v6
	s_mov_b32 s57, 0x2
	v_add_u32_e32 v83, v4, v5
	s_branch .LcvqA_1381

; #define LAS __attribute__((address_space(3)))
; __device__ __forceinline__ int opaque_tid() { int t = threadIdx.x; asm volatile("" : "+v"(t)); return t; }
; __device__ __forceinline__ void cv_pair(const PT& a, LAS unsigned char* lds, int l, int r, int wave, int lane) {
;     LAS float* s0 = (LAS float*)(lds + wave * CV_WAVE_B); LAS float* s1 = (LAS float*)(lds + wave * CV_WAVE_B + CV_TILE_B);
;     const bool two = r + 1 < IT_LAYER;
;     const CvItem i0 = cv_decode(a, l, r), i1 = cv_decode(a, l, two ? r + 1 : r);
;     f32x4 v0[8], v1[8]; float g0[8], g1[8];
;     cv_load(i0, lane, v0, g0); cv_load(i1, lane, v1, g1);
;     cv_lds_write(s0, lane, v0, g0); cv_lds_write(s1, lane, v1, g1);
; __global__ void __launch_bounds__(NTHREADS, 2) mk_fwd(Args args) {
;     ...
;             if (l + 1 < DEPTH && !(G >= 256 && bid < 128)) { __syncthreads(); const int tid_ = opaque_tid(); convert_layer_queue(pt, lds, l + 1, cvq, tid_ >> 6, tid_ & 63); }
.LBB0_1377:
	s_cmp_eq_u32 s64, 3
	v_readlane_b32 s2, v253, 61
	s_cselect_b64 s[0:1], -1, 0
	v_readlane_b32 s3, v253, 62
	s_or_b64 s[0:1], s[2:3], s[0:1]
	v_readlane_b32 s2, v252, 4
	s_cmp_lg_u32 s2, 0x100
	s_cselect_b64 s[2:3], -1, 0
	s_or_b64 s[0:1], s[0:1], s[2:3]
	v_readlane_b32 s28, v254, 55
	s_mov_b32 s36, s64
	s_and_b64 vcc, exec, s[0:1]
	v_readlane_b32 s29, v254, 56
	s_cbranch_vccnz .LBB0_1470
	v_readlane_b32 s0, v254, 53
	v_readlane_b32 s1, v254, 54
	s_mov_b32 s3, s1
	s_lshl_b32 s2, s36, 6
	s_lshl_b64 s[0:1], s[2:3], 2
	v_readlane_b32 s4, v254, 60
	v_readlane_b32 s5, v254, 61
	s_add_u32 s0, s4, s0
	s_addc_u32 s1, s5, s1
	s_add_u32 s0, s0, 0x8000
	s_addc_u32 s1, s1, 0
	s_add_i32 s2, s36, 1
	s_mul_hi_u32 s33, s2, 0x2c00000
	s_mul_i32 s34, s2, 0x2c00000
	s_mul_hi_u32 s35, s2, 0x1600000
	s_mul_i32 s50, s2, 0x1600000
	s_lshl_b32 s6, s2, 11
	s_mov_b32 s7, s3
	s_lshl_b64 s[8:9], s[2:3], 24
	s_lshl_b64 s[10:11], s[2:3], 23
	s_mul_hi_u32 s51, s2, 0xc00000
	s_mul_i32 s52, s2, 0xc00000
	s_mul_hi_u32 s53, s2, 0x7280000
	s_mul_i32 s54, s2, 0x7280000
	s_mul_hi_u32 s55, s2, 0x3a00000
	v_writelane_b32 v254, s2, 53
	v_mov_b32_e32 v2, v0
	s_mul_i32 s56, s2, 0x3a00000
	v_writelane_b32 v254, s3, 54
	s_waitcnt vmcnt(0) lgkmcnt(0)
	s_barrier
	s_movk_i32 s2, 0x4200
	v_lshrrev_b32_e32 v1, 6, v2
	v_and_b32_e32 v3, 63, v2
	v_readfirstlane_b32 s100, v1
	v_readlane_b32 s101, v252, 0
	s_sub_u32 s101, s101, 128
	s_lshl_b32 s101, s101, 3
	s_add_u32 s100, s100, s101
	s_lshl_b32 s100, s100, 1
	s_add_u32 s100, s100, 0x1800
	v_mul_lo_u32 v1, v1, s2
	v_cmp_eq_u32_e64 s[40:41], 0, v3
	v_add_u32_e32 v3, 0, v1
	v_lshlrev_b32_e32 v1, 2, v2
	v_and_b32_e32 v66, 28, v1
	v_bfe_u32 v1, v2, 3, 3
	v_lshlrev_b32_e32 v2, 3, v2
	v_and_b32_e32 v68, 56, v2
	v_lshl_add_u32 v4, v66, 2, v3
	v_mul_u32_u24_e32 v5, 0x84, v1
	v_mul_u32_u24_e32 v2, 0x84, v68
	v_lshlrev_b32_e32 v6, 2, v1
	v_or_b32_e32 v67, 8, v1
	v_or_b32_e32 v69, 16, v1
	v_or_b32_e32 v71, 24, v1
	v_or_b32_e32 v73, 32, v1
	v_or_b32_e32 v75, 40, v1
	v_or_b32_e32 v77, 48, v1
	v_or_b32_e32 v79, 56, v1
	v_add3_u32 v81, v3, v2, v6
	s_mov_b32 s57, 0x1
	v_add_u32_e32 v83, v4, v5
	s_branch .LBB0_1381

; #define LAS __attribute__((address_space(3)))
; __device__ __forceinline__ void cv_pair(const PT& a, LAS unsigned char* lds, int l, int r, int wave, int lane) {
;     LAS float* s0 = (LAS float*)(lds + wave * CV_WAVE_B); LAS float* s1 = (LAS float*)(lds + wave * CV_WAVE_B + CV_TILE_B);
;     const bool two = r + 1 < IT_LAYER;
;     const CvItem i0 = cv_decode(a, l, r), i1 = cv_decode(a, l, two ? r + 1 : r);
;     f32x4 v0[8], v1[8]; float g0[8], g1[8];
;     cv_load(i0, lane, v0, g0); cv_load(i1, lane, v1, g1);
;     cv_lds_write(s0, lane, v0, g0); cv_lds_write(s1, lane, v1, g1);
;     for (int it = 0; it < budget; ++it) {
;         unsigned r = 0; if (lane == 0) r = __hip_atomic_fetch_add(ctr, 2u, __ATOMIC_RELAXED, __HIP_MEMORY_SCOPE_AGENT);
;         r = (unsigned)__builtin_amdgcn_readfirstlane((int)r) + (unsigned)CV_PRO_ITEMS;
;         if (r >= (unsigned)IT_LAYER) break;
;         cv_pair(a, lds, l, (int)r, wave, lane);
;     }
; }
.LBB0_1843:
	v_readlane_b32 s2, v252, 4
	s_cmp_lg_u32 s2, 0x100
	s_cbranch_scc1 .LcvqB_skip
	v_readlane_b32 s2, v252, 0
	s_cmp_lt_u32 s2, 128
	s_cbranch_scc1 .LcvqB_skip
	s_cmp_gt_u32 s36, 2
	s_cbranch_scc1 .LcvqB_skip
	v_writelane_b32 v255, s0, 8
	v_writelane_b32 v255, s1, 9
	v_writelane_b32 v255, s40, 10
	v_writelane_b32 v255, s41, 11
	s_mov_b32 s64, s36
	v_readlane_b32 s0, v254, 53
	v_readlane_b32 s1, v254, 54
	s_mov_b32 s3, s1
	s_lshl_b32 s2, s36, 6
	s_lshl_b64 s[0:1], s[2:3], 2
	v_readlane_b32 s4, v254, 60
	v_readlane_b32 s5, v254, 61
	s_add_u32 s0, s4, s0
	s_addc_u32 s1, s5, s1
	s_add_u32 s0, s0, 0x8000
	s_addc_u32 s1, s1, 0
	s_add_i32 s2, s36, 1
	s_mul_hi_u32 s33, s2, 0x2c00000
	s_mul_i32 s34, s2, 0x2c00000
	s_mul_hi_u32 s35, s2, 0x1600000
	s_mul_i32 s50, s2, 0x1600000
	s_lshl_b32 s6, s2, 11
	s_mov_b32 s7, s3
	s_lshl_b64 s[8:9], s[2:3], 24
	s_lshl_b64 s[10:11], s[2:3], 23
	s_mul_hi_u32 s51, s2, 0xc00000
	s_mul_i32 s52, s2, 0xc00000
	s_mul_hi_u32 s53, s2, 0x7280000
	s_mul_i32 s54, s2, 0x7280000
	s_mul_hi_u32 s55, s2, 0x3a00000
	v_writelane_b32 v254, s2, 53
	v_mov_b32_e32 v2, v0
	s_mul_i32 s56, s2, 0x3a00000
	v_writelane_b32 v254, s3, 54
	s_waitcnt vmcnt(0) lgkmcnt(0)
	s_barrier
	s_movk_i32 s2, 0x4200
	v_lshrrev_b32_e32 v1, 6, v2
	v_and_b32_e32 v3, 63, v2
	v_readfirstlane_b32 s100, v1
	v_readlane_b32 s101, v252, 0
	s_sub_u32 s101, s101, 128
	s_lshl_b32 s101, s101, 3
	s_add_u32 s100, s100, s101
	s_lshl_b32 s100, s100, 1
	s_add_u32 s100, s100, 0x2000
	v_mul_lo_u32 v1, v1, s2
	v_cmp_eq_u32_e64 s[40:41], 0, v3
	v_add_u32_e32 v3, 0, v1
	v_lshlrev_b32_e32 v1, 2, v2
	v_and_b32_e32 v66, 28, v1
	v_bfe_u32 v1, v2, 3, 3
	v_lshlrev_b32_e32 v2, 3, v2
	v_and_b32_e32 v68, 56, v2
	v_lshl_add_u32 v4, v66, 2, v3
	v_mul_u32_u24_e32 v5, 0x84, v1
	v_mul_u32_u24_e32 v2, 0x84, v68
	v_lshlrev_b32_e32 v6, 2, v1
	v_or_b32_e32 v67, 8, v1
	v_or_b32_e32 v69, 16, v1
	v_or_b32_e32 v71, 24, v1
	v_or_b32_e32 v73, 32, v1
	v_or_b32_e32 v75, 40, v1
	v_or_b32_e32 v77, 48, v1
	v_or_b32_e32 v79, 56, v1
	v_add3_u32 v81, v3, v2, v6
	s_mov_b32 s57, 0x1
	v_add_u32_e32 v83, v4, v5
	s_branch .LcvqB_1381
